# mixer: 96 instead of 64 workgroups start on the sample-attention queue (3 of every 8 groups of 8), on top of the stacked file
# baseline (speedup 1.0000x reference)
; #define LAS __attribute__((address_space(3)))
; #define Q_POP(var, word) do { if (tid == 0) MISC[0] = __hip_atomic_fetch_add(ctl + CW_QHEAD + (word), 1u, RLX_AGENT); __syncthreads(); var = (int)MISC[0]; __syncthreads(); var = __builtin_amdgcn_readfirstlane(var); } while (0)
; #define DUP_SEL(n) DUP_CAT(DUP_, n)
; #define P (*args_here())
; #define SEAM(k) do { if (IN(k) && IN((k) + 1)) xcd_barrier(bar); } while (0)
; template <int MODE, int VAR> DI void mixer_phase(const Ptrs& P, LAS unsigned char* lds, volatile LAS unsigned* MISC, gu32* ctl, int tid, int wave, int lane) {
;     unsigned char* ws = P.ws;
;     const bf16* QB = (const bf16*)(ws + WS_QB); const bf16* CKVB = (const bf16*)(ws + WS_CKVB); const bf16* KRB = (const bf16*)(ws + WS_KRB);
;     const float* SC5 = (const float*)(ws + WS_SC5); const float* RKV = (const float*)(ws + WS_RKV); const float* SCAL = (const float*)(ws + WS_SCAL); float* Y = (float*)(ws + WS_Y);
;     ...
;     int is_ = Q_SATT, it;
;     if ((MODE == 0) && ((blockIdx.x >> 3) & 7) < MK_SFRAC8) {
;         Q_POP(is_, 16);
;         while (is_ < Q_SATT) {
;             att::sample_unit(lds, QB, CKVB, KRB, P.in[2], P.in[3], (const int*)P.in[6], (float*)(ws + WS_PO), (float*)(ws + WS_PML), is_ >> 1, is_ & 1, tid, wave, lane);
;             Q_POP(is_, 16); }
;     }
;     Q_POP(it, 0);
; __global__ void __launch_bounds__(NWAVES * 64, 2) mk_fwd(Args args) {
;     ...
;     if (IN(8)) { mixer_phase<0, 0>(P, lds, MISC, ctl, tid, wave, lane); DUP_SEL(MK_REP_MIX)(mixer_phase<MK_DUP_MODE, MK_DUP_VAR>(P, lds, MISC, ctl + 128, tid, wave, lane);) SEAM(8); }
.LBB0_940:
	s_cmp_lt_i32 s46, 9
	s_cselect_b64 s[0:1], -1, 0
	s_cmp_gt_i32 s47, 8
	s_cselect_b64 s[2:3], -1, 0
	s_and_b64 s[0:1], s[0:1], s[2:3]
	s_andn2_b64 vcc, exec, s[0:1]
	s_cbranch_vccnz .LBB0_1362
	s_mov_b64 s[84:85], s[96:97]
	s_load_dwordx2 s[82:83], s[84:85], 0x130
	s_waitcnt lgkmcnt(0)
	s_add_u32 s0, s82, 0x3ee00000
	s_addc_u32 s1, s83, 0
	v_writelane_b32 v254, s0, 17
	s_nop 1
	v_writelane_b32 v254, s1, 18
	s_add_u32 s0, s82, 0x44100000
	s_addc_u32 s1, s83, 0
	v_writelane_b32 v254, s0, 19
	s_nop 1
	v_writelane_b32 v254, s1, 20
	s_add_u32 s0, s82, 0x44a00000
	s_addc_u32 s1, s83, 0
	v_writelane_b32 v254, s0, 21
	s_nop 1
	v_writelane_b32 v254, s1, 22
	s_bfe_u32 s0, s33, 0x30003
	s_cmp_ge_u32 s0, 3
	s_cbranch_scc1 .LBB0_1001
	v_cmp_eq_u32_e64 s[2:3], 0, v0
	s_and_saveexec_b64 s[4:5], s[2:3]
	s_cbranch_execz .LBB0_946
	s_mov_b64 s[8:9], exec
	v_mbcnt_lo_u32_b32 v1, s8, 0
	v_mbcnt_hi_u32_b32 v1, s9, v1
	v_cmp_eq_u32_e32 vcc, 0, v1
	s_and_saveexec_b64 s[6:7], vcc
	s_cbranch_execz .LBB0_945
	s_bcnt1_i32_b64 s0, s[8:9]
	s_waitcnt vmcnt(0)
	v_mov_b32_e32 v2, 0
	v_mov_b32_e32 v3, s0
	global_atomic_add v2, v2, v3, s[44:45] offset:320 sc0
